# attention: query blocks that reuse the shared key-norm bound also skip the cross-wave max reduction (2 barriers, 16 LDS reads)
# speedup vs baseline: 1.0091x; 1.0015x over previous
.Lkm_ready:
	global_load_dwordx2 v[46:47], v133, s[24:25] offset:8 sc1
	v_lshlrev_b32_e32 v17, 2, v43
	v_xor_b32_e32 v16, 32, v17
	v_xor_b32_e32 v114, 64, v17
	v_xor_b32_e32 v115, 0x80, v17
	v_and_b32_e32 v22, 0xffff0000, v13
	v_mul_f32_e32 v22, v22, v22
	s_waitcnt vmcnt(0)
	v_mov_b32_e32 v18, v46
	v_mov_b32_e32 v19, v47
	v_mov_b32_e32 v20, v47
	v_mov_b32_e32 v21, v47
	s_branch .Lkm_b3

.LBB0_120:
	s_or_b64 exec, exec, s[4:5]
	v_readlane_b32 s4, v254, 9
	v_mov_b32_e32 v18, s69
	s_waitcnt lgkmcnt(0)
	v_mov_b32_e32 v19, s4
	s_barrier
	ds_read_b32 v18, v18
	ds_read_b32 v19, v19
	v_readlane_b32 s4, v254, 10
	v_and_b32_e32 v22, 0xffff0000, v13
	v_mul_f32_e32 v22, v22, v22
	s_waitcnt lgkmcnt(1)
	v_max_f32_e32 v18, v18, v18
	s_waitcnt lgkmcnt(0)
	v_max_f32_e32 v19, v19, v19
	v_max_f32_e32 v18, v18, v19
	v_mov_b32_e32 v19, s4
	v_readlane_b32 s4, v254, 11
	ds_read_b32 v19, v19
	s_mov_b32 s24, 0xf800000
	v_mov_b32_e32 v20, s4
	ds_read_b32 v20, v20
	v_readlane_b32 s4, v254, 12
	s_waitcnt lgkmcnt(0)
	v_max3_f32 v18, v18, v19, v20
	v_mov_b32_e32 v19, s4
	v_readlane_b32 s4, v254, 13
	ds_read_b32 v19, v19
	s_nop 0
	v_mov_b32_e32 v20, s4
	ds_read_b32 v20, v20
	v_readlane_b32 s4, v254, 14
	s_waitcnt lgkmcnt(0)
	v_max3_f32 v18, v18, v19, v20
	v_mov_b32_e32 v19, s4
	v_readlane_b32 s4, v254, 15
	ds_read_b32 v19, v19
	s_nop 0
	v_mov_b32_e32 v20, s4
	ds_read_b32 v20, v20
	v_readlane_b32 s4, v254, 16
	s_waitcnt lgkmcnt(0)
	v_max3_f32 v18, v18, v19, v20
	v_mov_b32_e32 v19, s4
	v_readlane_b32 s4, v254, 17
	ds_read_b32 v19, v19
	s_waitcnt lgkmcnt(0)
	v_max_f32_e32 v19, v19, v19
	v_mov_b32_e32 v20, s4
	ds_read_b32 v20, v20
	v_readlane_b32 s4, v254, 18
	s_waitcnt lgkmcnt(0)
	v_max_f32_e32 v20, v20, v20
	v_max_f32_e32 v19, v19, v20
	v_mov_b32_e32 v20, s4
	v_readlane_b32 s4, v254, 19
	ds_read_b32 v20, v20
	s_nop 0
	v_mov_b32_e32 v21, s4
	ds_read_b32 v21, v21
	v_readlane_b32 s4, v254, 20
	s_waitcnt lgkmcnt(0)
	v_max3_f32 v19, v19, v20, v21
	v_mov_b32_e32 v20, s4
	v_readlane_b32 s4, v254, 21
	ds_read_b32 v20, v20
	s_nop 0
	v_mov_b32_e32 v21, s4
	ds_read_b32 v21, v21
	v_readlane_b32 s4, v254, 22
	s_waitcnt lgkmcnt(0)
	v_max3_f32 v19, v19, v20, v21
	v_mov_b32_e32 v20, s4
	v_readlane_b32 s4, v254, 23
	ds_read_b32 v20, v20
	s_nop 0
	v_mov_b32_e32 v21, s4
	ds_read_b32 v21, v21
	s_waitcnt lgkmcnt(0)
	s_branch .Lkm_b3n
.Lkm_b3:
	s_mov_b32 s24, 0xf800000
.Lkm_b3n:
	s_barrier
	v_max3_f32 v20, v19, v20, v21
	s_cmpk_lt_i32 s37, 0x100
	s_cselect_b32 s25, 15, 1
	s_and_b32 s25, s25, s37
	s_cmp_lg_u32 s25, 0
	s_cbranch_scc1 .Lkm_nopub
	s_lshr_b32 s4, s37, 4
	s_add_i32 s5, s37, 0xffffff00
	s_lshr_b32 s5, s5, 1
	s_add_i32 s5, s5, 16
	s_cmpk_lt_i32 s37, 0x100
	s_cselect_b32 s4, s4, s5
	s_mul_i32 s5, s40, 0x90
	s_add_i32 s4, s4, s5
	s_lshl_b32 s4, s4, 4
	s_add_u32 s4, s12, s4
	s_addc_u32 s5, s13, 0
	s_sub_u32 s4, s4, 0x9c02000
	s_subb_u32 s5, s5, 0
	v_cmp_eq_u32_e32 vcc, 0, v40
	s_and_b64 exec, exec, vcc
	v_mov_b32_e32 v46, v18
	v_mov_b32_e32 v47, v20
	global_store_dwordx2 v133, v[46:47], s[4:5] offset:8 sc1
	s_waitcnt vmcnt(0)
	v_mov_b32_e32 v45, 1
	global_store_dword v133, v45, s[4:5] sc1
	s_mov_b64 exec, -1
